# attention B far-tile loop: same deferred O/l rescale as A (threshold 4 log2 units, wave-uniform skip)
# speedup vs baseline: 1.0107x; 1.0020x over previous
; #define LAS __attribute__((address_space(3)))
; template <int DQK, bool MB> ...
;     ...
;             for (int kk = 0; kk < KK; ++kk) kfa[kk] = *(const LAS bf16x8*)(kb + kk * 1024 + koff);
; #pragma unroll
;             for (int ks = 0; ks < 4; ++ks) {
;                 if (ks < 3) {
; #pragma unroll
;                     for (int kk = 0; kk < KK; ++kk) { const bf16x8 t = *(const LAS bf16x8*)(kb + ((ks + 1) * KK + kk) * 1024 + koff); if (ks & 1) kfa[kk] = t; else kfb[kk] = t; }
;                 }
;                 __builtin_amdgcn_sched_barrier(0);
;                 s[ks][0] = (f32x4){0.f, 0.f, 0.f, 0.f}; s[ks][1] = (f32x4){0.f, 0.f, 0.f, 0.f};
; #pragma unroll
;                 for (int kk = 0; kk < KK; ++kk) { const bf16x8 kf = (ks & 1) ? kfb[kk] : kfa[kk];
;                     const bf16x8 qa0 = qf[0][kk], qa1 = qf[1][kk];
;                     s[ks][0] = __builtin_amdgcn_mfma_f32_16x16x32_bf16(kf, qa0, s[ks][0], 0, 0, 0);
;                     s[ks][1] = __builtin_amdgcn_mfma_f32_16x16x32_bf16(kf, qa1, s[ks][1], 0, 0, 0); }
;                 __builtin_amdgcn_sched_barrier(0);
;             }
;         }
;         if (ST) { asm volatile("" ::: "memory"); __builtin_amdgcn_s_barrier(); asm volatile("" ::: "memory"); }
;         if (act) {
;             if (MB) {
;                 const unsigned long long mw0 = sm0[kt], mw1 = sm1[kt];
;                 if (pass == 0) {
; #pragma unroll
;                     for (int ks = 0; ks < 4; ++ks) { const unsigned b0 = (unsigned)(mw0 >> (16 * ks + 4 * q)) & 0xFu, b1 = (unsigned)(mw1 >> (16 * ks + 4 * q)) & 0xFu;
; #pragma unroll
;                         for (int j = 0; j < 4; ++j) { s[ks][0][j] = ((b0 >> j) & 1u) ? s[ks][0][j] + tbfar : -INFINITY; s[ks][1][j] = ((b1 >> j) & 1u) ? s[ks][1][j] + tbfar : -INFINITY; } }
.LBB0_665:
	v_lshl_add_u32 v156, s45, 14, v181
	ds_read_b128 v[124:127], v156
	ds_read_b128 v[128:131], v156 offset:1024
	ds_read_b128 v[132:135], v156 offset:2048
	ds_read_b128 v[136:139], v156 offset:3072
	ds_read_b128 v[140:143], v156 offset:4096
	ds_read_b128 v[160:163], v156 offset:5120
	ds_read_b128 v[164:167], v156 offset:6144
	ds_read_b128 v[186:189], v156 offset:7168
	s_waitcnt lgkmcnt(7)
	v_mfma_f32_16x16x32_bf16 v[190:193], v[124:127], v[44:47], 0
	v_mfma_f32_16x16x32_bf16 v[124:127], v[124:127], v[60:63], 0
	s_waitcnt lgkmcnt(6)
	v_mfma_f32_16x16x32_bf16 v[190:193], v[128:131], v[64:67], v[190:193]
	v_mfma_f32_16x16x32_bf16 v[124:127], v[128:131], v[72:75], v[124:127]
	s_waitcnt lgkmcnt(5)
	v_mfma_f32_16x16x32_bf16 v[128:131], v[132:135], v[68:71], v[190:193]
	v_mfma_f32_16x16x32_bf16 v[124:127], v[132:135], v[76:79], v[124:127]
	s_waitcnt lgkmcnt(4)
	v_mfma_f32_16x16x32_bf16 v[128:131], v[136:139], v[80:83], v[128:131]
	v_mfma_f32_16x16x32_bf16 v[124:127], v[136:139], v[56:59], v[124:127]
	ds_read_b128 v[132:135], v156 offset:8192
	ds_read_b128 v[136:139], v156 offset:9216
	ds_read_b128 v[190:193], v156 offset:10240
	ds_read_b128 v[194:197], v156 offset:11264
	s_waitcnt lgkmcnt(7)
	v_mfma_f32_16x16x32_bf16 v[198:201], v[140:143], v[44:47], 0
	v_mfma_f32_16x16x32_bf16 v[140:143], v[140:143], v[60:63], 0
	s_waitcnt lgkmcnt(6)
	v_mfma_f32_16x16x32_bf16 v[198:201], v[160:163], v[64:67], v[198:201]
	v_mfma_f32_16x16x32_bf16 v[140:143], v[160:163], v[72:75], v[140:143]
	s_waitcnt lgkmcnt(5)
	v_mfma_f32_16x16x32_bf16 v[160:163], v[164:167], v[68:71], v[198:201]
	v_mfma_f32_16x16x32_bf16 v[140:143], v[164:167], v[76:79], v[140:143]
	s_waitcnt lgkmcnt(4)
	v_mfma_f32_16x16x32_bf16 v[160:163], v[186:189], v[80:83], v[160:163]
	v_mfma_f32_16x16x32_bf16 v[140:143], v[186:189], v[56:59], v[140:143]
	ds_read_b128 v[164:167], v156 offset:12288
	ds_read_b128 v[186:189], v156 offset:13312
	ds_read_b128 v[198:201], v156 offset:14336
	ds_read_b128 v[202:205], v156 offset:15360
	s_waitcnt lgkmcnt(7)
	v_mfma_f32_16x16x32_bf16 v[206:209], v[132:135], v[44:47], 0
	v_mfma_f32_16x16x32_bf16 v[132:135], v[132:135], v[60:63], 0
	s_waitcnt lgkmcnt(6)
	v_mfma_f32_16x16x32_bf16 v[206:209], v[136:139], v[64:67], v[206:209]
	v_mfma_f32_16x16x32_bf16 v[132:135], v[136:139], v[72:75], v[132:135]
	s_waitcnt lgkmcnt(5)
	v_mfma_f32_16x16x32_bf16 v[136:139], v[190:193], v[68:71], v[206:209]
	v_mfma_f32_16x16x32_bf16 v[132:135], v[190:193], v[76:79], v[132:135]
	s_waitcnt lgkmcnt(4)
	v_mfma_f32_16x16x32_bf16 v[136:139], v[194:197], v[80:83], v[136:139]
	v_mfma_f32_16x16x32_bf16 v[132:135], v[194:197], v[56:59], v[132:135]
	s_waitcnt lgkmcnt(3)
	v_mfma_f32_16x16x32_bf16 v[190:193], v[164:167], v[44:47], 0
	v_mfma_f32_16x16x32_bf16 v[164:167], v[164:167], v[60:63], 0
	s_waitcnt lgkmcnt(2)
	v_mfma_f32_16x16x32_bf16 v[164:167], v[186:189], v[72:75], v[164:167]
	v_mfma_f32_16x16x32_bf16 v[190:193], v[186:189], v[64:67], v[190:193]
	s_waitcnt lgkmcnt(1)
	v_mfma_f32_16x16x32_bf16 v[164:167], v[198:201], v[76:79], v[164:167]
	v_mfma_f32_16x16x32_bf16 v[186:189], v[198:201], v[68:71], v[190:193]
	s_waitcnt lgkmcnt(0)
	v_mfma_f32_16x16x32_bf16 v[164:167], v[202:205], v[56:59], v[164:167]
	v_mfma_f32_16x16x32_bf16 v[186:189], v[202:205], v[80:83], v[186:189]
	v_mov_b32_e32 v156, s4
	s_nop 0
	ds_read2_b64 v[190:193], v156 offset1:32
	s_nop 3
	v_add_f32_e32 v158, v113, v164
	v_add_f32_e32 v164, v113, v165
	v_add_f32_e32 v132, v113, v132
	v_add_f32_e32 v124, v113, v124
	s_waitcnt lgkmcnt(0)
	v_lshrrev_b64 v[156:157], v150, v[192:193]
	v_and_b32_e32 v157, 1, v156
	v_cmp_eq_u32_e32 vcc, 1, v157
	v_and_b32_e32 v157, 2, v156
	v_add_f32_e32 v126, v113, v126
	v_cndmask_b32_e32 v168, v155, v158, vcc
	v_cmp_ne_u32_e32 vcc, 0, v157
	v_and_b32_e32 v158, 4, v156
	v_add_f32_e32 v157, v113, v166
	v_cndmask_b32_e32 v169, v155, v164, vcc
	v_cmp_ne_u32_e32 vcc, 0, v158
	v_and_b32_e32 v156, 8, v156
	v_add_f32_e32 v127, v113, v127
	v_cndmask_b32_e32 v166, v155, v157, vcc
	v_add_f32_e32 v157, v113, v167
	v_cmp_ne_u32_e32 vcc, 0, v156
	s_mul_i32 s47, s45, 0x4400
	s_nop 0
	v_cndmask_b32_e32 v185, v155, v157, vcc
	v_lshrrev_b64 v[156:157], v150, v[190:191]
	v_and_b32_e32 v158, 1, v156
	v_add_f32_e32 v157, v113, v186
	v_cmp_eq_u32_e32 vcc, 1, v158
	v_and_b32_e32 v164, 2, v156
	v_and_b32_e32 v165, 4, v156
	v_cndmask_b32_e32 v158, v155, v157, vcc
	v_add_f32_e32 v157, v113, v187
	v_cmp_ne_u32_e32 vcc, 0, v164
	v_and_b32_e32 v156, 8, v156
	s_nop 0
	v_cndmask_b32_e32 v164, v155, v157, vcc
	v_add_f32_e32 v157, v113, v188
	v_cmp_ne_u32_e32 vcc, 0, v165
	s_nop 1
	v_cndmask_b32_e32 v167, v155, v157, vcc
	v_add_f32_e32 v157, v113, v189
	v_cmp_ne_u32_e32 vcc, 0, v156
	s_nop 1
	v_cndmask_b32_e32 v183, v155, v157, vcc
	v_lshrrev_b64 v[156:157], v152, v[192:193]
	v_and_b32_e32 v157, 1, v156
	v_cmp_eq_u32_e32 vcc, 1, v157
	s_nop 1
	v_cndmask_b32_e32 v186, v155, v132, vcc
	v_add_f32_e32 v132, v113, v133
	v_and_b32_e32 v133, 2, v156
	v_cmp_ne_u32_e32 vcc, 0, v133
	v_and_b32_e32 v133, 4, v156
	s_nop 0
	v_cndmask_b32_e32 v187, v155, v132, vcc
	v_add_f32_e32 v132, v113, v134
	v_cmp_ne_u32_e32 vcc, 0, v133
	v_and_b32_e32 v133, 8, v156
	s_nop 0
	v_cndmask_b32_e32 v188, v155, v132, vcc
	v_add_f32_e32 v132, v113, v135
	v_cmp_ne_u32_e32 vcc, 0, v133
	s_nop 1
	v_cndmask_b32_e32 v189, v155, v132, vcc
	v_lshrrev_b64 v[132:133], v152, v[190:191]
	v_and_b32_e32 v134, 1, v132
	v_add_f32_e32 v133, v113, v136
	v_cmp_eq_u32_e32 vcc, 1, v134
	v_and_b32_e32 v135, 2, v132
	s_nop 0
	v_cndmask_b32_e32 v134, v155, v133, vcc
	v_add_f32_e32 v133, v113, v137
	v_cmp_ne_u32_e32 vcc, 0, v135
	v_and_b32_e32 v135, 4, v132
	v_and_b32_e32 v132, 8, v132
; template <int DQK, bool MB> ...
;     ...
;                     for (int ks = 0; ks < 4; ++ks) { const unsigned b0 = (unsigned)(mw0 >> (16 * ks + 4 * q)) & 0xFu, b1 = (unsigned)(mw1 >> (16 * ks + 4 * q)) & 0xFu;
; #pragma unroll
;                         for (int j = 0; j < 4; ++j) { s[ks][0][j] = ((b0 >> j) & 1u) ? s[ks][0][j] + tbfar : -INFINITY; s[ks][1][j] = ((b1 >> j) & 1u) ? s[ks][1][j] + tbfar : -INFINITY; } }
;                 } else
;                 {
;                 float bv[4][2][4];
; #pragma unroll
;                 for (int ks = 0; ks < 4; ++ks) { const i32x4 pk = *(const i32x4*)(posb + 64 * kt + 16 * ks + 4 * q);
; #pragma unroll
;                     for (int j = 0; j < 4; ++j) { const int d0 = min(max(pt0 - pk[j], 0), 128), d1 = min(max(pt1 - pk[j], 0), 128);
;                         bv[ks][0][j] = tb[d0 * 16 + r]; bv[ks][1][j] = tb[d1 * 16 + r]; } }
;                 __builtin_amdgcn_sched_barrier(0);
; #pragma unroll
;                 for (int ks = 0; ks < 4; ++ks) { const unsigned b0 = (unsigned)(mw0 >> (16 * ks + 4 * q)) & 0xFu, b1 = (unsigned)(mw1 >> (16 * ks + 4 * q)) & 0xFu;
; #pragma unroll
;                     for (int j = 0; j < 4; ++j) { s[ks][0][j] = ((b0 >> j) & 1u) ? s[ks][0][j] + bv[ks][0][j] : -INFINITY; s[ks][1][j] = ((b1 >> j) & 1u) ? s[ks][1][j] + bv[ks][1][j] : -INFINITY; } }
;                 }
;             } else if (64 * kt + 63 > wave_qmax - 31) {
; #pragma unroll
;                 for (int ks = 0; ks < 4; ++ks)
; #pragma unroll
;                     for (int j = 0; j < 4; ++j) { const int key = 64 * kt + 16 * ks + 4 * q + j;
;                         s[ks][0][j] = (key <= qi0) ? s[ks][0][j] : -INFINITY; s[ks][1][j] = (key <= qi1) ? s[ks][1][j] : -INFINITY; }
;             }
;             float alpha2[2];
; #pragma unroll
;             for (int ct = 0; ct < 2; ++ct) {
;                 float mx = -INFINITY;
; #pragma unroll
;                 for (int ks = 0; ks < 4; ++ks)
; #pragma unroll
;                     for (int j = 0; j < 4; ++j) mx = fmaxf(mx, s[ks][ct][j]);
;                 mx = fmaxf(mx, __shfl_xor(mx, 16)); mx = fmaxf(mx, __shfl_xor(mx, 32));
;                 const float mnew = fmaxf(mrow[ct], mx), alpha = __builtin_amdgcn_exp2f(mrow[ct] - mnew);
;                 mrow[ct] = mnew;
;                 float ps = 0.f;
; #pragma unroll
;                 for (int ks = 0; ks < 4; ++ks)
; #pragma unroll
	v_cndmask_b32_e32 v136, v155, v133, vcc
	v_add_f32_e32 v133, v113, v138
	v_cmp_ne_u32_e32 vcc, 0, v135
	v_lshrrev_b32_e32 v135, v154, v192
	v_and_b32_e32 v135, 1, v135
	v_cndmask_b32_e32 v138, v155, v133, vcc
	v_add_f32_e32 v133, v113, v139
	v_cmp_ne_u32_e32 vcc, 0, v132
	s_nop 1
	v_cndmask_b32_e32 v156, v155, v133, vcc
	v_lshrrev_b64 v[132:133], v154, v[192:193]
	v_add_f32_e32 v133, v113, v140
	v_cmp_eq_u32_e32 vcc, 1, v135
	v_and_b32_e32 v135, 2, v132
	s_nop 0
	v_cndmask_b32_e32 v194, v155, v133, vcc
	v_add_f32_e32 v133, v113, v141
	v_cmp_ne_u32_e32 vcc, 0, v135
	v_and_b32_e32 v135, 4, v132
	v_and_b32_e32 v132, 8, v132
	v_cndmask_b32_e32 v195, v155, v133, vcc
	v_add_f32_e32 v133, v113, v142
	v_cmp_ne_u32_e32 vcc, 0, v135
	v_lshrrev_b32_e32 v135, v154, v190
	v_and_b32_e32 v135, 1, v135
	v_cndmask_b32_e32 v196, v155, v133, vcc
	v_add_f32_e32 v133, v113, v143
	v_cmp_ne_u32_e32 vcc, 0, v132
	s_nop 1
	v_cndmask_b32_e32 v197, v155, v133, vcc
	v_lshrrev_b64 v[132:133], v154, v[190:191]
	v_add_f32_e32 v133, v113, v160
	v_cmp_eq_u32_e32 vcc, 1, v135
	v_and_b32_e32 v137, 2, v132
	s_nop 0
	v_cndmask_b32_e32 v135, v155, v133, vcc
	v_add_f32_e32 v133, v113, v161
	v_cmp_ne_u32_e32 vcc, 0, v137
	v_and_b32_e32 v137, 4, v132
	v_and_b32_e32 v132, 8, v132
	v_cndmask_b32_e32 v140, v155, v133, vcc
	v_add_f32_e32 v133, v113, v162
	v_cmp_ne_u32_e32 vcc, 0, v137
	s_nop 1
	v_cndmask_b32_e32 v142, v155, v133, vcc
	v_add_f32_e32 v133, v113, v163
	v_cmp_ne_u32_e32 vcc, 0, v132
	s_nop 1
	v_cndmask_b32_e32 v160, v155, v133, vcc
	v_lshrrev_b64 v[132:133], v179, v[192:193]
	v_lshrrev_b32_e32 v133, v179, v192
	v_and_b32_e32 v133, 1, v133
	v_cmp_eq_u32_e32 vcc, 1, v133
	v_and_b32_e32 v133, 4, v132
	s_nop 0
	v_cndmask_b32_e32 v162, v155, v124, vcc
	v_add_f32_e32 v124, v113, v125
	v_and_b32_e32 v125, 2, v132
	v_cmp_ne_u32_e32 vcc, 0, v125
	v_and_b32_e32 v132, 8, v132
	s_nop 0
	v_cndmask_b32_e32 v192, v155, v124, vcc
	v_lshrrev_b64 v[124:125], v179, v[190:191]
	v_add_f32_e32 v125, v113, v128
	v_lshrrev_b32_e32 v128, v179, v190
	v_and_b32_e32 v128, 1, v128
	v_cmp_eq_u32_e32 vcc, 1, v128
	v_add_f32_e32 v128, v113, v129
	v_and_b32_e32 v129, 2, v124
	v_cndmask_b32_e32 v125, v155, v125, vcc
	v_cmp_ne_u32_e32 vcc, 0, v129
	v_add_f32_e32 v129, v113, v130
	v_and_b32_e32 v130, 4, v124
	v_cndmask_b32_e32 v128, v155, v128, vcc
	v_cmp_ne_u32_e32 vcc, 0, v130
	v_and_b32_e32 v124, 8, v124
	v_add_f32_e32 v130, v113, v131
	v_cndmask_b32_e32 v129, v155, v129, vcc
	v_cmp_ne_u32_e32 vcc, 0, v124
	s_nop 1
	v_cndmask_b32_e32 v124, v155, v130, vcc
	v_max3_f32 v130, v125, s79, v128
	v_max3_f32 v130, v130, v129, v124
	v_max3_f32 v130, v130, v135, v140
	v_max3_f32 v130, v130, v142, v160
	v_max3_f32 v130, v130, v134, v136
	v_max3_f32 v130, v130, v138, v156
	v_max3_f32 v130, v130, v158, v164
	v_max3_f32 v130, v130, v167, v183
	ds_bpermute_b32 v131, v159, v130
	v_cmp_ne_u32_e32 vcc, 0, v133
	s_waitcnt lgkmcnt(0)
	v_max_f32_e32 v131, v131, v131
	v_max_f32_e32 v130, v130, v131
	ds_bpermute_b32 v131, v184, v130
	v_cndmask_b32_e32 v126, v155, v126, vcc
	v_cmp_ne_u32_e32 vcc, 0, v132
	s_waitcnt lgkmcnt(0)
	v_max3_f32 v182, v123, v130, v131
	v_sub_f32_e32 v241, v182, v123
	v_cmp_lt_f32_e64 s[98:99], 4.0, v241
	s_nop 1
	v_cndmask_b32_e64 v182, v123, v182, s[98:99]
	v_sub_f32_e32 v130, v123, v182
	v_sub_f32_e32 v123, v125, v182
	v_cndmask_b32_e32 v132, v155, v127, vcc
	v_exp_f32_e32 v157, v123
	v_sub_f32_e32 v123, v128, v182
	v_max3_f32 v128, v162, s79, v192
	v_max3_f32 v128, v128, v126, v132
	v_exp_f32_e32 v143, v123
	v_sub_f32_e32 v123, v129, v182
	v_max3_f32 v128, v128, v194, v195
	v_exp_f32_e32 v141, v123
	v_sub_f32_e32 v123, v124, v182
	v_max3_f32 v128, v128, v196, v197
	v_exp_f32_e32 v139, v123
	v_sub_f32_e32 v123, v135, v182
	v_max3_f32 v128, v128, v186, v187
	v_exp_f32_e32 v137, v123
	v_sub_f32_e32 v123, v140, v182
	v_max3_f32 v128, v128, v188, v189
	v_exp_f32_e32 v135, v123
	v_sub_f32_e32 v123, v142, v182
	v_max3_f32 v128, v128, v168, v169
	v_exp_f32_e32 v133, v123
	v_sub_f32_e32 v123, v160, v182
	v_max3_f32 v128, v128, v166, v185
	v_exp_f32_e32 v131, v123
	v_sub_f32_e32 v123, v134, v182
	ds_bpermute_b32 v134, v159, v128
	v_sub_f32_e32 v124, v158, v182
	v_exp_f32_e32 v165, v124
	v_sub_f32_e32 v124, v164, v182
	v_exp_f32_e32 v161, v124
	s_waitcnt lgkmcnt(0)
	v_max_f32_e32 v134, v134, v134
	v_max_f32_e32 v128, v128, v134
	ds_bpermute_b32 v134, v184, v128
	v_sub_f32_e32 v124, v167, v182
	v_exp_f32_e32 v129, v123
	v_sub_f32_e32 v123, v136, v182
	v_exp_f32_e32 v167, v124
	v_sub_f32_e32 v124, v183, v182
	s_waitcnt lgkmcnt(0)
	v_max3_f32 v183, v122, v128, v134
	v_sub_f32_e32 v242, v183, v122
	v_cmp_lt_f32_e64 s[100:101], 4.0, v242
	s_nop 1
	v_cndmask_b32_e64 v183, v122, v183, s[100:101]
	v_exp_f32_e32 v127, v123
	v_sub_f32_e32 v123, v138, v182
	v_sub_f32_e32 v190, v122, v183
	v_sub_f32_e32 v122, v162, v183
	v_exp_f32_e32 v125, v123
	v_sub_f32_e32 v123, v156, v182
	v_exp_f32_e32 v156, v122
	v_sub_f32_e32 v122, v192, v183
	v_exp_f32_e32 v142, v122
	v_sub_f32_e32 v122, v126, v183
	v_exp_f32_e32 v140, v122
	v_sub_f32_e32 v122, v132, v183
	v_exp_f32_e32 v138, v122
	v_sub_f32_e32 v122, v194, v183
	v_exp_f32_e32 v136, v122
	v_sub_f32_e32 v122, v195, v183
	v_exp_f32_e32 v134, v122
	v_sub_f32_e32 v122, v196, v183
	v_sub_f32_e32 v160, v168, v183
	v_exp_f32_e32 v168, v190
	v_exp_f32_e32 v132, v122
	v_sub_f32_e32 v122, v197, v183
	v_exp_f32_e32 v158, v130
	v_exp_f32_e32 v130, v122
	v_sub_f32_e32 v122, v186, v183
	v_exp_f32_e32 v128, v122
	v_sub_f32_e32 v122, v187, v183
	v_exp_f32_e32 v126, v122
	v_sub_f32_e32 v122, v188, v183
	v_exp_f32_e32 v164, v160
	v_sub_f32_e32 v160, v169, v183
	v_sub_f32_e32 v162, v166, v183
	v_add_u32_e32 v169, s47, v180
	v_exp_f32_e32 v163, v124
	v_exp_f32_e32 v124, v122
	v_sub_f32_e32 v122, v189, v183
	v_exp_f32_e32 v166, v162
	v_sub_f32_e32 v162, v185, v183
	v_add_u32_e32 v185, 0x8000, v169
	v_add_u32_e32 v222, 0x8800, v169
	v_add_u32_e32 v223, 0x9000, v169
	v_add_u32_e32 v225, 0x9800, v169
	v_add_u32_e32 v230, 0xa000, v169
	v_add_u32_e32 v231, 0xa800, v169
	v_add_u32_e32 v232, 0xb000, v169
	v_add_u32_e32 v169, 0xb800, v169
	v_exp_f32_e32 v123, v123
	v_exp_f32_e32 v122, v122
	v_exp_f32_e32 v160, v160
	v_exp_f32_e32 v162, v162
	s_or_b64 s[98:99], s[98:99], s[100:101]
	s_cmp_eq_u64 s[98:99], 0
	s_cbranch_scc1 .Llazy_bf_skip
; #define LAS __attribute__((address_space(3)))
; DI unsigned pk2(float lo, float hi) { f32v2 v = {lo, hi}; bf16v2 b = __builtin_convertvector(v, bf16v2); return __builtin_bit_cast(unsigned, b); }
; template <int DQK, bool MB> ...
;     ...
;             {
; #pragma unroll
;                 for (int ct = 0; ct < 2; ++ct)
; #pragma unroll
;                     for (int dt = 0; dt < 8; ++dt) o[ct][dt] *= alpha2[ct];
;             }
; #pragma unroll
;             for (int kb2 = 0; kb2 < 2; ++kb2) {
;                 bf16x8 pb[2];
; #pragma unroll
;                 for (int ct = 0; ct < 2; ++ct) { u32x4 w; w.x = pk2(s[2 * kb2][ct][0], s[2 * kb2][ct][1]); w.y = pk2(s[2 * kb2][ct][2], s[2 * kb2][ct][3]);
;                     w.z = pk2(s[2 * kb2 + 1][ct][0], s[2 * kb2 + 1][ct][1]); w.w = pk2(s[2 * kb2 + 1][ct][2], s[2 * kb2 + 1][ct][3]); pb[ct] = __builtin_bit_cast(bf16x8, w); }
;                 bf16x8 vf[8];
; #pragma unroll
;                 for (int dt = 0; dt < 8; ++dt) { const LAS unsigned char* vp = vb + (16 * dt + r) * VT_PITCH + (32 * kb2 + 4 * q) * 2;
;                     const s16x4 lo = *(const LAS s16x4*)vp, hi = *(const LAS s16x4*)(vp + 32);
;                     vf[dt] = __builtin_shufflevector(lo, hi, 0, 1, 2, 3, 4, 5, 6, 7); }
;                 __builtin_amdgcn_sched_barrier(0);
; #pragma unroll
;                 for (int dt = 0; dt < 8; ++dt) {
;                     o[0][dt] = __builtin_amdgcn_mfma_f32_16x16x32_bf16(vf[dt], pb[0], o[0][dt], 0, 0, 0);
;                     o[1][dt] = __builtin_amdgcn_mfma_f32_16x16x32_bf16(vf[dt], pb[1], o[1][dt], 0, 0, 0); }
;                 __builtin_amdgcn_sched_barrier(0);
;             }
;         }
;         if (pre) { const int nb = ST ? ((buf == 0) ? 2 : buf - 1) : (buf ^ 1); LAS unsigned char* kbn = kbase + nb * KT_BYTES; LAS unsigned char* vbn = vbase + nb * VT_BYTES;
; #pragma unroll
;             for (int i = 0; i < KCH; ++i) *(LAS u32x4*)(kbn + klo0 + 2048 * i) = kreg[i];
; #pragma unroll
;             for (int i = 0; i < 2; ++i) { *(LAS u32x2*)(vbn + vlo0 + 64 * VT_PITCH * i) = (u32x2){vreg[i].x, vreg[i].y}; *(LAS u32x2*)(vbn + vlo0 + 64 * VT_PITCH * i + 8) = (u32x2){vreg[i].z, vreg[i].w}; } }
;         __syncthreads();
;         buf = ST ? ((buf == 2) ? 0 : buf + 1) : (buf ^ 1);
	v_pk_mul_f32 v[30:31], v[30:31], v[168:169] op_sel_hi:[1,0]
	v_pk_mul_f32 v[28:29], v[28:29], v[168:169] op_sel_hi:[1,0]
	v_pk_mul_f32 v[26:27], v[26:27], v[168:169] op_sel_hi:[1,0]
	v_pk_mul_f32 v[24:25], v[24:25], v[168:169] op_sel_hi:[1,0]
	v_pk_mul_f32 v[22:23], v[22:23], v[168:169] op_sel_hi:[1,0]
	v_pk_mul_f32 v[20:21], v[20:21], v[168:169] op_sel_hi:[1,0]
	v_pk_mul_f32 v[18:19], v[18:19], v[168:169] op_sel_hi:[1,0]
	v_pk_mul_f32 v[16:17], v[16:17], v[168:169] op_sel_hi:[1,0]
	v_pk_mul_f32 v[14:15], v[14:15], v[168:169] op_sel_hi:[1,0]
	v_pk_mul_f32 v[12:13], v[12:13], v[168:169] op_sel_hi:[1,0]
	v_pk_mul_f32 v[10:11], v[10:11], v[168:169] op_sel_hi:[1,0]
	v_pk_mul_f32 v[8:9], v[8:9], v[168:169] op_sel_hi:[1,0]
	v_pk_mul_f32 v[6:7], v[6:7], v[168:169] op_sel_hi:[1,0]
	v_pk_mul_f32 v[4:5], v[4:5], v[168:169] op_sel_hi:[1,0]
	v_pk_mul_f32 v[2:3], v[2:3], v[168:169] op_sel_hi:[1,0]
	v_pk_mul_f32 v[0:1], v[0:1], v[168:169] op_sel_hi:[1,0]
	v_pk_mul_f32 v[110:111], v[110:111], v[158:159] op_sel_hi:[1,0]
	v_pk_mul_f32 v[108:109], v[108:109], v[158:159] op_sel_hi:[1,0]
	v_pk_mul_f32 v[106:107], v[106:107], v[158:159] op_sel_hi:[1,0]
	v_pk_mul_f32 v[104:105], v[104:105], v[158:159] op_sel_hi:[1,0]
	v_pk_mul_f32 v[102:103], v[102:103], v[158:159] op_sel_hi:[1,0]
	v_pk_mul_f32 v[100:101], v[100:101], v[158:159] op_sel_hi:[1,0]
	v_pk_mul_f32 v[98:99], v[98:99], v[158:159] op_sel_hi:[1,0]
	v_pk_mul_f32 v[96:97], v[96:97], v[158:159] op_sel_hi:[1,0]
	v_pk_mul_f32 v[86:87], v[86:87], v[158:159] op_sel_hi:[1,0]
	v_pk_mul_f32 v[84:85], v[84:85], v[158:159] op_sel_hi:[1,0]
	v_pk_mul_f32 v[42:43], v[42:43], v[158:159] op_sel_hi:[1,0]
	v_pk_mul_f32 v[40:41], v[40:41], v[158:159] op_sel_hi:[1,0]
	v_pk_mul_f32 v[38:39], v[38:39], v[158:159] op_sel_hi:[1,0]
	v_pk_mul_f32 v[36:37], v[36:37], v[158:159] op_sel_hi:[1,0]
	v_pk_mul_f32 v[34:35], v[34:35], v[158:159] op_sel_hi:[1,0]
	v_pk_mul_f32 v[32:33], v[32:33], v[158:159] op_sel_hi:[1,0]
.Llazy_bf_skip:
	ds_read2_b64 v[190:193], v185 offset1:4
	ds_read2_b64 v[194:197], v222 offset0:16 offset1:20
	ds_read2_b64 v[198:201], v223 offset0:32 offset1:36
	ds_read2_b64 v[202:205], v225 offset0:48 offset1:52
	ds_read2_b64 v[206:209], v230 offset0:64 offset1:68
	ds_read2_b64 v[210:213], v231 offset0:80 offset1:84
	ds_read2_b64 v[214:217], v232 offset0:96 offset1:100
	ds_read2_b64 v[218:221], v169 offset0:112 offset1:116
	v_cvt_pk_bf16_f32 v186, v157, v143
	v_cvt_pk_bf16_f32 v187, v141, v139
	v_cvt_pk_bf16_f32 v188, v137, v135
	v_cvt_pk_bf16_f32 v189, v133, v131
	v_cvt_pk_bf16_f32 v226, v156, v142
	v_cvt_pk_bf16_f32 v227, v140, v138
	v_cvt_pk_bf16_f32 v228, v136, v134
	v_cvt_pk_bf16_f32 v229, v132, v130
	s_waitcnt lgkmcnt(7)
	v_mfma_f32_16x16x32_bf16 v[108:111], v[190:193], v[186:189], v[108:111]
	v_mfma_f32_16x16x32_bf16 v[28:31], v[190:193], v[226:229], v[28:31]
	s_waitcnt lgkmcnt(6)
	v_mfma_f32_16x16x32_bf16 v[104:107], v[194:197], v[186:189], v[104:107]
	v_mfma_f32_16x16x32_bf16 v[24:27], v[194:197], v[226:229], v[24:27]
	s_waitcnt lgkmcnt(5)
	v_mfma_f32_16x16x32_bf16 v[100:103], v[198:201], v[186:189], v[100:103]
	v_mfma_f32_16x16x32_bf16 v[20:23], v[198:201], v[226:229], v[20:23]
	s_waitcnt lgkmcnt(4)
	v_mfma_f32_16x16x32_bf16 v[96:99], v[202:205], v[186:189], v[96:99]
	v_mfma_f32_16x16x32_bf16 v[16:19], v[202:205], v[226:229], v[16:19]
	s_waitcnt lgkmcnt(3)
	v_mfma_f32_16x16x32_bf16 v[84:87], v[206:209], v[186:189], v[84:87]
	v_mfma_f32_16x16x32_bf16 v[12:15], v[206:209], v[226:229], v[12:15]
	s_waitcnt lgkmcnt(2)
	v_mfma_f32_16x16x32_bf16 v[40:43], v[210:213], v[186:189], v[40:43]
	v_mfma_f32_16x16x32_bf16 v[8:11], v[210:213], v[226:229], v[8:11]
	s_waitcnt lgkmcnt(1)
	v_mfma_f32_16x16x32_bf16 v[36:39], v[214:217], v[186:189], v[36:39]
	v_mfma_f32_16x16x32_bf16 v[4:7], v[214:217], v[226:229], v[4:7]
	s_waitcnt lgkmcnt(0)
	v_mfma_f32_16x16x32_bf16 v[32:35], v[218:221], v[186:189], v[32:35]
	v_mfma_f32_16x16x32_bf16 v[0:3], v[218:221], v[226:229], v[0:3]
	ds_read2_b64 v[190:193], v185 offset0:8 offset1:12
	ds_read2_b64 v[194:197], v222 offset0:24 offset1:28
	ds_read2_b64 v[198:201], v223 offset0:40 offset1:44
	ds_read2_b64 v[202:205], v225 offset0:56 offset1:60
	ds_read2_b64 v[206:209], v230 offset0:72 offset1:76
	ds_read2_b64 v[210:213], v231 offset0:88 offset1:92
	ds_read2_b64 v[214:217], v232 offset0:104 offset1:108
	ds_read2_b64 v[218:221], v169 offset0:120 offset1:124
	v_cvt_pk_bf16_f32 v186, v129, v127
	v_cvt_pk_bf16_f32 v187, v125, v123
	v_cvt_pk_bf16_f32 v188, v165, v161
	v_cvt_pk_bf16_f32 v189, v167, v163
	v_cvt_pk_bf16_f32 v226, v128, v126
	v_cvt_pk_bf16_f32 v227, v124, v122
	v_cvt_pk_bf16_f32 v228, v164, v160
	v_cvt_pk_bf16_f32 v229, v166, v162
	s_waitcnt lgkmcnt(7)
	v_mfma_f32_16x16x32_bf16 v[108:111], v[190:193], v[186:189], v[108:111]
	v_mfma_f32_16x16x32_bf16 v[28:31], v[190:193], v[226:229], v[28:31]
	s_waitcnt lgkmcnt(6)
	v_mfma_f32_16x16x32_bf16 v[104:107], v[194:197], v[186:189], v[104:107]
	v_mfma_f32_16x16x32_bf16 v[24:27], v[194:197], v[226:229], v[24:27]
	s_waitcnt lgkmcnt(5)
	v_mfma_f32_16x16x32_bf16 v[100:103], v[198:201], v[186:189], v[100:103]
	v_mfma_f32_16x16x32_bf16 v[20:23], v[198:201], v[226:229], v[20:23]
	s_waitcnt lgkmcnt(4)
	v_mfma_f32_16x16x32_bf16 v[96:99], v[202:205], v[186:189], v[96:99]
	v_mfma_f32_16x16x32_bf16 v[16:19], v[202:205], v[226:229], v[16:19]
	s_waitcnt lgkmcnt(3)
	v_mfma_f32_16x16x32_bf16 v[84:87], v[206:209], v[186:189], v[84:87]
	v_mfma_f32_16x16x32_bf16 v[12:15], v[206:209], v[226:229], v[12:15]
	s_waitcnt lgkmcnt(2)
	v_mfma_f32_16x16x32_bf16 v[40:43], v[210:213], v[186:189], v[40:43]
	v_mfma_f32_16x16x32_bf16 v[8:11], v[210:213], v[226:229], v[8:11]
	s_waitcnt lgkmcnt(1)
	v_mfma_f32_16x16x32_bf16 v[36:39], v[214:217], v[186:189], v[36:39]
	v_mfma_f32_16x16x32_bf16 v[4:7], v[214:217], v[226:229], v[4:7]
	s_waitcnt lgkmcnt(0)
	v_mfma_f32_16x16x32_bf16 v[32:35], v[218:221], v[186:189], v[32:35]
	v_mfma_f32_16x16x32_bf16 v[0:3], v[218:221], v[226:229], v[0:3]
	s_andn2_b64 vcc, exec, s[0:1]
	s_xor_b32 s45, s45, 1
	s_cbranch_vccnz .LBB0_667
	v_lshl_add_u32 v169, s45, 14, v178
	s_mul_i32 s0, s45, 0x4400
	s_waitcnt vmcnt(3)
	ds_write_b128 v169, v[48:51]
	s_waitcnt vmcnt(2)
	ds_write_b128 v169, v[52:55] offset:2048
	v_add_u32_e32 v169, s0, v177
	v_add_u32_e32 v185, 0x8000, v169
	v_add_u32_e32 v169, 0xa200, v169
	s_waitcnt vmcnt(1)
	ds_write2_b64 v185, v[88:89], v[90:91] offset1:1
	s_waitcnt vmcnt(0)
	ds_write2_b64 v169, v[92:93], v[94:95] offset1:1
